# idle workgroups of the P5 tail prefetch 100 MB of x toward the memory-side cache for P6 (plain loads, P6 x loads stay non-temporal)
# speedup vs baseline: 1.0046x; 1.0046x over previous
; #define LAS __attribute__((address_space(3)))
; __global__ void __launch_bounds__(NWAVES * 64, 2) mk_fwd(Args args) {
;     ...
;         if (F.G == 256 && (int)blockIdx.x >= 64) {
;             const int lb = (int)blockIdx.x - 64;
;             if (F.wave < 4) gemv_item(c, c_ctx, ada_w, ada_b, mod, 768 + lb * 4 + F.wave, threadIdx.x & 63);
;             else tr_run(args, 2, lb * 4 + (F.wave - 4), 192 * 4, threadIdx.x & 63, (LAS float*)(F.lds + F.wave * 16384));
;         }
;     ...
;             for (int q = 0; q < 3; ++q) { const int row = row0 + q; const float* src = row < ML ? x + (size_t)row * DM : ctx + (size_t)(row - ML) * DM; load_row_f32(src, F.lane, v[q]);
.LBB0_666:
	s_cmpk_lg_i32 s63, 0x100
	s_cbranch_scc1 .Lpf6_skip
	s_cmp_lt_i32 s2, 64
	s_cbranch_scc1 .Lpf6_skip
	v_readlane_b32 s8, v247, 34
	v_readlane_b32 s9, v247, 35
	v_lshlrev_b32_e32 v0, 4, v198
	s_sub_i32 s6, s2, 64
	s_lshl_b32 s6, s6, 13
	v_add_u32_e32 v0, s6, v0
	s_movk_i32 s7, 64
.Lpf6_loop:
	global_load_dwordx4 v[4:7], v0, s[8:9]
	v_add_u32_e32 v0, 0x180000, v0
	s_sub_u32 s7, s7, 1
	s_cmp_lg_u32 s7, 0
	s_cbranch_scc1 .Lpf6_loop
